# SB unit: gate-row loads hoisted ahead of the key loop into spare VGPRs
# speedup vs baseline: 1.0091x; 1.0004x over previous
.LBB0_351:
	v_lshlrev_b64 v[120:121], 6, v[0:1]
	v_lshl_add_u64 v[186:187], v[120:121], 1, s[2:3]
	v_lshlrev_b64 v[188:189], 1, v[114:115]
	s_mov_b64 s[6:7], 0x3000000
	v_lshl_add_u64 v[186:187], v[186:187], 0, v[188:189]
	v_lshl_add_u64 v[186:187], v[186:187], 0, s[6:7]
	global_load_dwordx4 v[192:195], v[186:187], off
	global_load_dwordx4 v[218:221], v[186:187], off offset:64
	global_load_dwordx4 v[222:225], v[186:187], off offset:32
	global_load_dwordx4 v[240:243], v[186:187], off offset:96
	s_mov_b32 s95, s68
	v_cmp_eq_u32_e64 s[70:71], 0, v82
	s_and_saveexec_b64 s[6:7], s[70:71]
	v_cndmask_b32_e64 v82, 0, 1, s[4:5]
	v_mov_b32_e32 v84, s94
	ds_write_b32 v84, v82
	s_or_b64 exec, exec, s[6:7]
	s_and_b32 s4, s66, 0x7fffffc0
	v_add_u32_e32 v82, s4, v83
	v_sub_u32_e32 v82, v0, v82
	v_cmp_lt_i32_e64 s[8:9], 26, v82
	v_cmp_lt_i32_e64 s[40:41], 58, v82
	v_cmp_lt_i32_e64 s[4:5], 27, v82
	v_cmp_lt_i32_e64 s[6:7], 59, v82
	v_cmp_lt_i32_e64 s[10:11], 25, v82
	v_cmp_lt_i32_e64 s[42:43], 57, v82
	s_or_b64 s[8:9], s[4:5], s[8:9]
	s_or_b64 s[40:41], s[6:7], s[40:41]
	v_cmp_lt_i32_e64 s[12:13], 24, v82
	v_cmp_lt_i32_e64 s[44:45], 56, v82
	s_or_b64 s[10:11], s[8:9], s[10:11]
	s_or_b64 s[42:43], s[40:41], s[42:43]
	v_cmp_lt_i32_e64 s[14:15], 19, v82
	v_cmp_lt_i32_e64 s[46:47], 51, v82
	s_or_b64 s[12:13], s[10:11], s[12:13]
	s_or_b64 s[44:45], s[42:43], s[44:45]
	v_cmp_lt_i32_e64 s[16:17], 18, v82
	v_cmp_lt_i32_e64 s[48:49], 50, v82
	s_or_b64 s[14:15], s[12:13], s[14:15]
	s_or_b64 s[46:47], s[44:45], s[46:47]
	v_cmp_lt_i32_e64 s[18:19], 17, v82
	v_cmp_lt_i32_e64 s[50:51], 49, v82
	s_or_b64 s[16:17], s[14:15], s[16:17]
	s_or_b64 s[48:49], s[46:47], s[48:49]
	v_cmp_lt_i32_e64 s[20:21], 16, v82
	v_cmp_lt_i32_e64 s[52:53], 48, v82
	s_or_b64 s[18:19], s[16:17], s[18:19]
	s_or_b64 s[50:51], s[48:49], s[50:51]
	v_cmp_lt_i32_e64 s[22:23], 11, v82
	v_cmp_lt_i32_e64 s[54:55], 43, v82
	s_or_b64 s[20:21], s[18:19], s[20:21]
	s_or_b64 s[52:53], s[50:51], s[52:53]
	v_cmp_lt_i32_e64 s[24:25], 10, v82
	v_cmp_lt_i32_e64 s[56:57], 42, v82
	s_or_b64 s[22:23], s[20:21], s[22:23]
	s_or_b64 s[54:55], s[52:53], s[54:55]
	v_cmp_lt_i32_e64 s[26:27], 9, v82
	v_cmp_lt_i32_e64 s[58:59], 41, v82
	s_or_b64 s[24:25], s[22:23], s[24:25]
	s_or_b64 s[56:57], s[54:55], s[56:57]
	v_cmp_lt_i32_e64 s[28:29], 8, v82
	v_cmp_lt_i32_e64 s[60:61], 40, v82
	s_or_b64 s[26:27], s[24:25], s[26:27]
	s_or_b64 s[58:59], s[56:57], s[58:59]
	v_cmp_lt_i32_e64 s[30:31], 3, v82
	v_cmp_lt_i32_e64 s[62:63], 35, v82
	s_or_b64 s[28:29], s[26:27], s[28:29]
	s_or_b64 s[60:61], s[58:59], s[60:61]
	v_cmp_lt_i32_e64 s[34:35], 2, v82
	v_cmp_lt_i32_e64 s[64:65], 34, v82
	s_or_b64 s[30:31], s[28:29], s[30:31]
	s_or_b64 s[62:63], s[60:61], s[62:63]
	v_cmp_lt_i32_e64 s[36:37], 1, v82
	v_cmp_lt_i32_e64 s[66:67], 33, v82
	s_or_b64 s[34:35], s[30:31], s[34:35]
	s_or_b64 s[64:65], s[62:63], s[64:65]
	v_cmp_lt_i32_e32 vcc, 0, v82
	v_cmp_lt_i32_e64 s[68:69], 32, v82
	s_lshl_b32 s38, s99, 2
	s_or_b64 s[36:37], s[34:35], s[36:37]
	s_or_b64 s[66:67], s[64:65], s[66:67]
	s_mov_b32 s86, 8
	s_sub_i32 s88, 30, s38
	s_sub_i32 s87, s0, s98
	s_mov_b32 s89, 0x10000
	s_or_b64 s[38:39], s[36:37], vcc
	s_or_b64 s[68:69], s[66:67], s[68:69]
	s_branch .LBB0_356

.LBB0_384:
	s_or_b64 exec, exec, s[4:5]
	v_lshl_add_u64 v[34:35], v[120:121], 1, s[2:3]
	s_waitcnt lgkmcnt(9)
	v_lshlrev_b64 v[46:47], 1, v[114:115]
	v_lshl_add_u64 v[34:35], v[34:35], 0, v[46:47]
	s_mov_b64 s[2:3], 0x3000000
	v_lshl_add_u64 v[36:37], v[34:35], 0, s[2:3]
	v_add_co_u32_e32 v34, vcc, 0x3000000, v34
	v_readlane_b32 s2, v255, 49
	s_nop 0
	v_addc_co_u32_e32 v35, vcc, 0, v35, vcc
	s_waitcnt lgkmcnt(7)
	s_nop 0
	v_lshl_add_u32 v0, s2, 11, v0
	s_waitcnt lgkmcnt(6)
	v_lshlrev_b64 v[52:53], 11, v[0:1]
	v_readlane_b32 s2, v255, 50
	v_lshl_add_u64 v[52:53], s[56:57], 0, v[52:53]
	s_lshl_b32 s80, s2, 7
	v_lshl_add_u64 v[52:53], v[52:53], 0, s[80:81]
	v_lshl_add_u64 v[46:47], v[52:53], 0, v[46:47]
	s_waitcnt vmcnt(0) lgkmcnt(0)
	s_barrier
	v_min_u32_e32 v253, 0xffff, v253
	v_or_b32_e32 v95, v95, v253
	v_mov_b32_e32 v48, v192
	v_mov_b32_e32 v49, v193
	v_mov_b32_e32 v50, v194
	v_mov_b32_e32 v51, v195
	v_mov_b32_e32 v42, v218
	v_mov_b32_e32 v43, v219
	v_mov_b32_e32 v44, v220
	v_mov_b32_e32 v45, v221
	v_mov_b32_e32 v38, v222
	v_mov_b32_e32 v39, v223
	v_mov_b32_e32 v40, v224
	v_mov_b32_e32 v41, v225
	v_mov_b32_e32 v34, v240
	v_mov_b32_e32 v35, v241
	v_mov_b32_e32 v36, v242
	v_mov_b32_e32 v37, v243
	s_mov_b64 s[2:3], 0
	s_waitcnt vmcnt(3)
	v_mov_b32_e32 v0, v50
	s_nop 1
	v_permlane32_swap_b32_e32 v48, v0
	v_lshlrev_b32_e32 v50, 16, v48
	s_waitcnt lgkmcnt(3)
	v_mov_b32_e32 v54, v51
	v_and_b32_e32 v51, 0xffff0000, v48
	v_mul_f32_e32 v48, 0xbfb8aa3b, v50
	v_exp_f32_e32 v48, v48
	v_permlane32_swap_b32_e32 v49, v54
	v_add_f32_e32 v48, 1.0, v48
	v_rcp_f32_e32 v52, v48
	v_mul_f32_e32 v48, 0xbfb8aa3b, v51
	v_exp_f32_e32 v48, v48
	s_nop 0
	v_add_f32_e32 v48, 1.0, v48
	v_rcp_f32_e32 v53, v48
	v_lshlrev_b32_e32 v48, 16, v49
	v_and_b32_e32 v49, 0xffff0000, v49
	v_mul_f32 v50, v52, v50
	v_mul_f32 v51, v53, v51
	s_nop 0
	v_mul_f32 v18, v18, v50
	v_mul_f32 v19, v19, v51
	s_nop 0
	v_cvt_pk_bf16_f32 v18, v18, v19
	v_mul_f32_e32 v19, 0xbfb8aa3b, v48
	v_exp_f32_e32 v19, v19
	s_nop 0
	v_add_f32_e32 v19, 1.0, v19
	v_rcp_f32_e32 v50, v19
	v_mul_f32_e32 v19, 0xbfb8aa3b, v49
	v_exp_f32_e32 v19, v19
	s_nop 0
	v_add_f32_e32 v19, 1.0, v19
	v_rcp_f32_e32 v51, v19
	s_nop 0
	v_mul_f32 v48, v50, v48
	v_mul_f32 v49, v51, v49
	s_nop 0
	v_mul_f32 v20, v20, v48
	v_mul_f32 v21, v21, v49
	s_nop 0
	v_cvt_pk_bf16_f32 v19, v20, v21
	v_lshlrev_b32_e32 v20, 16, v0
	v_and_b32_e32 v21, 0xffff0000, v0
	v_mul_f32_e32 v0, 0xbfb8aa3b, v20
	v_exp_f32_e32 v0, v0
	s_nop 0
	v_add_f32_e32 v0, 1.0, v0
	v_rcp_f32_e32 v48, v0
	v_mul_f32_e32 v0, 0xbfb8aa3b, v21
	v_exp_f32_e32 v0, v0
	s_nop 0
	v_add_f32_e32 v0, 1.0, v0
	v_rcp_f32_e32 v49, v0
	s_nop 0
	v_mul_f32 v20, v48, v20
	v_mul_f32 v21, v49, v21
	s_nop 0
	v_mul_f32 v20, v22, v20
	v_mul_f32 v21, v23, v21
	v_lshlrev_b32_e32 v22, 16, v54
	v_mul_f32_e32 v0, 0xbfb8aa3b, v22
	v_exp_f32_e32 v0, v0
	v_and_b32_e32 v23, 0xffff0000, v54
	v_cvt_pk_bf16_f32 v20, v20, v21
	s_nop 1
	v_permlane32_swap_b32_e32 v18, v20
	v_add_f32_e32 v0, 1.0, v0
	v_rcp_f32_e32 v48, v0
	v_mul_f32_e32 v0, 0xbfb8aa3b, v23
	v_exp_f32_e32 v0, v0
	s_nop 0
	v_add_f32_e32 v0, 1.0, v0
	v_rcp_f32_e32 v49, v0
	s_waitcnt vmcnt(2)
	v_mov_b32_e32 v0, v44
	s_nop 1
	v_permlane32_swap_b32_e32 v42, v0
	v_mul_f32 v22, v48, v22
	v_mul_f32 v23, v49, v23
	s_nop 0
	v_mul_f32 v22, v24, v22
	v_mul_f32 v23, v25, v23
	s_nop 0
	v_cvt_pk_bf16_f32 v21, v22, v23
	s_nop 1
	v_permlane32_swap_b32_e32 v19, v21
	global_store_dwordx4 v[46:47], v[18:21], off
	v_mov_b32_e32 v22, v45
	s_nop 1
	v_permlane32_swap_b32_e32 v43, v22
	v_lshlrev_b32_e32 v18, 16, v42
	v_and_b32_e32 v19, 0xffff0000, v42
	v_mul_f32_e32 v20, 0xbfb8aa3b, v18
	v_mul_f32_e32 v21, 0xbfb8aa3b, v19
	v_exp_f32_e32 v20, v20
	v_exp_f32_e32 v21, v21
	v_add_f32_e32 v20, 1.0, v20
	v_add_f32_e32 v21, 1.0, v21
	v_rcp_f32_e32 v20, v20
	v_rcp_f32_e32 v21, v21
	s_nop 0
	v_mul_f32 v18, v20, v18
	v_mul_f32 v19, v21, v19
	s_nop 0
	v_mul_f32 v2, v2, v18
	v_mul_f32 v3, v3, v19
	v_lshlrev_b32_e32 v18, 16, v43
	v_cvt_pk_bf16_f32 v2, v2, v3
	v_mul_f32_e32 v3, 0xbfb8aa3b, v18
	v_exp_f32_e32 v3, v3
	v_and_b32_e32 v19, 0xffff0000, v43
	v_add_f32_e32 v3, 1.0, v3
	v_rcp_f32_e32 v20, v3
	v_mul_f32_e32 v3, 0xbfb8aa3b, v19
	v_exp_f32_e32 v3, v3
	s_nop 0
	v_add_f32_e32 v3, 1.0, v3
	v_rcp_f32_e32 v21, v3
	s_nop 0
	v_mul_f32 v18, v20, v18
	v_mul_f32 v19, v21, v19
	s_nop 0
	v_mul_f32 v4, v4, v18
	v_mul_f32 v5, v5, v19
	s_nop 0
	v_cvt_pk_bf16_f32 v3, v4, v5
	v_lshlrev_b32_e32 v4, 16, v0
	v_and_b32_e32 v5, 0xffff0000, v0
	v_mul_f32_e32 v0, 0xbfb8aa3b, v4
	v_exp_f32_e32 v0, v0
	s_nop 0
	v_add_f32_e32 v0, 1.0, v0
	v_rcp_f32_e32 v18, v0
	v_mul_f32_e32 v0, 0xbfb8aa3b, v5
	v_exp_f32_e32 v0, v0
	s_nop 0
	v_add_f32_e32 v0, 1.0, v0
	v_rcp_f32_e32 v19, v0
	s_nop 0
	v_mul_f32 v4, v18, v4
	v_mul_f32 v5, v19, v5
	s_nop 0
	v_mul_f32 v4, v6, v4
	v_mul_f32 v5, v7, v5
	v_lshlrev_b32_e32 v6, 16, v22
	v_mul_f32_e32 v0, 0xbfb8aa3b, v6
	v_exp_f32_e32 v0, v0
	v_and_b32_e32 v7, 0xffff0000, v22
	v_cvt_pk_bf16_f32 v4, v4, v5
	s_nop 1
	v_permlane32_swap_b32_e32 v2, v4
	v_add_f32_e32 v0, 1.0, v0
	v_rcp_f32_e32 v18, v0
	v_mul_f32_e32 v0, 0xbfb8aa3b, v7
	v_exp_f32_e32 v0, v0
	s_nop 0
	v_add_f32_e32 v0, 1.0, v0
	v_rcp_f32_e32 v19, v0
	s_waitcnt vmcnt(2)
	v_mov_b32_e32 v0, v40
	s_nop 1
	v_permlane32_swap_b32_e32 v38, v0
	v_mul_f32 v6, v18, v6
	v_mul_f32 v7, v19, v7
	s_nop 0
	v_mul_f32 v6, v8, v6
	v_mul_f32 v7, v9, v7
	v_mov_b32_e32 v8, v41
	v_cvt_pk_bf16_f32 v5, v6, v7
	s_nop 1
	v_permlane32_swap_b32_e32 v3, v5
	global_store_dwordx4 v[46:47], v[2:5], off offset:64
	v_permlane32_swap_b32_e32 v39, v8
	s_nop 0
	v_lshlrev_b32_e32 v2, 16, v38
	v_and_b32_e32 v3, 0xffff0000, v38
	v_mul_f32_e32 v4, 0xbfb8aa3b, v2
	v_mul_f32_e32 v5, 0xbfb8aa3b, v3
	v_exp_f32_e32 v4, v4
	v_exp_f32_e32 v5, v5
	v_add_f32_e32 v4, 1.0, v4
	v_add_f32_e32 v5, 1.0, v5
	v_rcp_f32_e32 v4, v4
	v_rcp_f32_e32 v5, v5
	s_nop 0
	v_mul_f32 v2, v4, v2
	v_mul_f32 v3, v5, v3
	s_nop 0
	v_mul_f32 v2, v26, v2
	v_mul_f32 v3, v27, v3
	v_lshlrev_b32_e32 v4, 16, v39
	v_cvt_pk_bf16_f32 v2, v2, v3
	v_mul_f32_e32 v3, 0xbfb8aa3b, v4
	v_exp_f32_e32 v3, v3
	v_and_b32_e32 v5, 0xffff0000, v39
	v_add_f32_e32 v3, 1.0, v3
	v_rcp_f32_e32 v6, v3
	v_mul_f32_e32 v3, 0xbfb8aa3b, v5
	v_exp_f32_e32 v3, v3
	s_nop 0
	v_add_f32_e32 v3, 1.0, v3
	v_rcp_f32_e32 v7, v3
	s_nop 0
	v_mul_f32 v4, v6, v4
	v_mul_f32 v5, v7, v5
	s_nop 0
	v_mul_f32 v4, v28, v4
	v_mul_f32 v5, v29, v5
	s_nop 0
	v_cvt_pk_bf16_f32 v3, v4, v5
	v_lshlrev_b32_e32 v4, 16, v0
	v_and_b32_e32 v5, 0xffff0000, v0
	v_mul_f32_e32 v0, 0xbfb8aa3b, v4
	v_exp_f32_e32 v0, v0
	s_nop 0
	v_add_f32_e32 v0, 1.0, v0
	v_rcp_f32_e32 v6, v0
	v_mul_f32_e32 v0, 0xbfb8aa3b, v5
	v_exp_f32_e32 v0, v0
	s_nop 0
	v_add_f32_e32 v0, 1.0, v0
	v_rcp_f32_e32 v7, v0
	s_nop 0
	v_mul_f32 v4, v6, v4
	v_mul_f32 v5, v7, v5
	v_lshlrev_b32_e32 v6, 16, v8
	v_mul_f32_e32 v0, 0xbfb8aa3b, v6
	v_exp_f32_e32 v0, v0
	v_and_b32_e32 v7, 0xffff0000, v8
	v_mul_f32 v4, v30, v4
	v_mul_f32 v5, v31, v5
	v_add_f32_e32 v0, 1.0, v0
	v_rcp_f32_e32 v8, v0
	v_mul_f32_e32 v0, 0xbfb8aa3b, v7
	v_exp_f32_e32 v0, v0
	v_cvt_pk_bf16_f32 v4, v4, v5
	s_nop 1
	v_permlane32_swap_b32_e32 v2, v4
	v_add_f32_e32 v0, 1.0, v0
	v_rcp_f32_e32 v9, v0
	s_waitcnt vmcnt(2)
	v_mov_b32_e32 v0, v36
	s_nop 1
	v_permlane32_swap_b32_e32 v34, v0
	v_mul_f32 v6, v8, v6
	v_mul_f32 v7, v9, v7
	v_mov_b32_e32 v8, v37
	v_mul_f32 v6, v32, v6
	v_mul_f32 v7, v33, v7
	s_nop 0
	v_permlane32_swap_b32_e32 v35, v8
	v_cvt_pk_bf16_f32 v5, v6, v7
	s_nop 1
	v_permlane32_swap_b32_e32 v3, v5
	global_store_dwordx4 v[46:47], v[2:5], off offset:32
	s_nop 1
	v_lshlrev_b32_e32 v2, 16, v34
	v_and_b32_e32 v3, 0xffff0000, v34
	v_mul_f32_e32 v4, 0xbfb8aa3b, v2
	v_mul_f32_e32 v5, 0xbfb8aa3b, v3
	v_exp_f32_e32 v4, v4
	v_exp_f32_e32 v5, v5
	v_add_f32_e32 v4, 1.0, v4
	v_add_f32_e32 v5, 1.0, v5
	v_rcp_f32_e32 v4, v4
	v_rcp_f32_e32 v5, v5
	s_nop 0
	v_mul_f32 v2, v4, v2
	v_mul_f32 v3, v5, v3
	s_nop 0
	v_mul_f32 v2, v10, v2
	v_mul_f32 v3, v11, v3
	v_lshlrev_b32_e32 v4, 16, v35
	v_cvt_pk_bf16_f32 v2, v2, v3
	v_mul_f32_e32 v3, 0xbfb8aa3b, v4
	v_exp_f32_e32 v3, v3
	v_and_b32_e32 v5, 0xffff0000, v35
	v_add_f32_e32 v3, 1.0, v3
	v_rcp_f32_e32 v6, v3
	v_mul_f32_e32 v3, 0xbfb8aa3b, v5
	v_exp_f32_e32 v3, v3
	s_nop 0
	v_add_f32_e32 v3, 1.0, v3
	v_rcp_f32_e32 v7, v3
	s_nop 0
	v_mul_f32 v4, v6, v4
	v_mul_f32 v5, v7, v5
	s_nop 0
	v_mul_f32 v4, v12, v4
	v_mul_f32 v5, v13, v5
	s_nop 0
	v_cvt_pk_bf16_f32 v3, v4, v5
	v_lshlrev_b32_e32 v4, 16, v0
	v_and_b32_e32 v5, 0xffff0000, v0
	v_mul_f32_e32 v0, 0xbfb8aa3b, v4
	v_exp_f32_e32 v0, v0
	s_nop 0
	v_add_f32_e32 v0, 1.0, v0
	v_rcp_f32_e32 v6, v0
	v_mul_f32_e32 v0, 0xbfb8aa3b, v5
	v_exp_f32_e32 v0, v0
	s_nop 0
	v_add_f32_e32 v0, 1.0, v0
	v_rcp_f32_e32 v7, v0
	s_nop 0
	v_mul_f32 v4, v6, v4
	v_mul_f32 v5, v7, v5
	v_lshlrev_b32_e32 v6, 16, v8
	v_mul_f32_e32 v0, 0xbfb8aa3b, v6
	v_exp_f32_e32 v0, v0
	v_and_b32_e32 v7, 0xffff0000, v8
	v_mul_f32 v4, v14, v4
	v_mul_f32 v5, v15, v5
	v_add_f32_e32 v0, 1.0, v0
	v_rcp_f32_e32 v8, v0
	v_mul_f32_e32 v0, 0xbfb8aa3b, v7
	v_exp_f32_e32 v0, v0
	v_cvt_pk_bf16_f32 v4, v4, v5
	s_nop 1
	v_permlane32_swap_b32_e32 v2, v4
	v_add_f32_e32 v0, 1.0, v0
	v_rcp_f32_e32 v9, v0
	s_nop 0
	v_mul_f32 v6, v8, v6
	v_mul_f32 v7, v9, v7
	s_nop 0
	v_mul_f32 v6, v16, v6
	v_mul_f32 v7, v17, v7
	s_nop 0
	v_cvt_pk_bf16_f32 v5, v6, v7
	s_nop 1
	v_permlane32_swap_b32_e32 v3, v5
	global_store_dwordx4 v[46:47], v[2:5], off offset:96
